# serpentine MFMA order in P1/P4 K loops: consecutive MFMAs share one operand fragment
# baseline (speedup 1.0000x reference)
; #define PG8_STAGE(bufoff, gbase, voff) do { _Pragma("unroll") for (int _i = 0; _i < 2; ++_i) \
;         __builtin_amdgcn_global_load_lds((const unsigned*)((const char*)(gbase) + (voff)[_i]), (LAS unsigned*)(lds + (bufoff) + ldsw + _i * 8192), 16, 0, 0); } while (0)
; #define PG8_LDA(dst, b, h) do { _Pragma("unroll") for (int m = 0; m < 4; ++m) _Pragma("unroll") for (int k = 0; k < 2; ++k) dst[m][k] = *(const LAS bf16x8*)(lds + PG8_SA(b, h) + aoff + m * 2048 + k * 1024); } while (0)
; #define PG8_LDB(dst, b, h) do { _Pragma("unroll") for (int n = 0; n < 2; ++n) _Pragma("unroll") for (int k = 0; k < 2; ++k) dst[n][k] = *(const LAS bf16x8*)(lds + PG8_SB(b, h) + boff + n * 2048 + k * 1024); } while (0)
; #define PG8_MMA(ai, bj, At, Bt) do { __builtin_amdgcn_s_setprio(1); _Pragma("unroll") for (int m = 0; m < 4; ++m) _Pragma("unroll") for (int n = 0; n < 2; ++n) _Pragma("unroll") for (int k = 0; k < 2; ++k) \
;         acc[ai][bj][m][n] = __builtin_amdgcn_mfma_f32_16x16x32_bf16(Bt[n][k], At[m][k], acc[ai][bj][m][n], 0, 0, 0); __builtin_amdgcn_s_setprio(0); } while (0)
; #define PG8_WAIT_V(n) asm volatile("s_waitcnt vmcnt(" #n ")" ::: "memory")
; #define PG8_WAIT_L(n) asm volatile("s_waitcnt lgkmcnt(" #n ")" ::: "memory")
; #define PG8_BAR __builtin_amdgcn_s_barrier()
; #define PG8_SCHED __builtin_amdgcn_sched_barrier(0)
; template <class Epi, class Sched, bool ALIGN_EPI, bool SP2, bool BPRE = false>
; __device__ __forceinline__ void gemm_phase(LAS unsigned char* lds, const int pitchA, const int pitchB, const Sched& S, const Epi& E) {
;     ...
;             PG8_LDB(B0, 0, 0); PG8_LDB(B1, 0, 1); PG8_SCHED; PG8_LDA(At, 0, 0); PG8_STAGE(PG8_SA(1, 1), a1 + hstepA, voffA);
;             PG8_WAIT_V(8); PG8_WAIT_L(0); PG8_BAR; PG8_MMA(0, 0, At, B0); PG8_MMA(0, 1, At, B1); PG8_BAR; PG8_SCHED;
;             PG8_LDA(At, 0, 1); PG8_STAGE(PG8_SB(0, 0), b2, voffB); PG8_STAGE(PG8_SB(0, 1), b2 + hstepB, voffB); PG8_STAGE(PG8_SA(0, 0), a2, voffA);
;             PG8_WAIT_V(8); PG8_WAIT_L(0); PG8_BAR; PG8_MMA(1, 0, At, B0); PG8_MMA(1, 1, At, B1); PG8_BAR; PG8_SCHED;
.LBB0_157:
	ds_read_b128 v[146:149], v158
	ds_read_b128 v[150:153], v158 offset:1024
	ds_read_b128 v[154:157], v158 offset:2048
	ds_read_b128 v[162:165], v158 offset:3072
	ds_read_b128 v[166:169], v159
	ds_read_b128 v[170:173], v159 offset:1024
	ds_read_b128 v[174:177], v159 offset:2048
	ds_read_b128 v[178:181], v159 offset:3072
	s_add_u32 s61, s66, 0xfff00080
	s_addc_u32 s63, s67, -1
	s_cmp_eq_u32 s59, 60
	s_cselect_b32 s71, s55, s63
	s_cselect_b32 s70, s54, s61
	s_cselect_b32 s69, s65, s6
	s_cselect_b32 s68, s64, s5
	v_lshl_add_u64 v[214:215], s[66:67], 0, v[142:143]
	s_add_i32 m0, s83, 0xc000
	ds_read_b128 v[182:185], v160
	ds_read_b128 v[186:189], v160 offset:1024
	ds_read_b128 v[190:193], v160 offset:2048
	ds_read_b128 v[194:197], v160 offset:3072
	ds_read_b128 v[198:201], v160 offset:4096
	ds_read_b128 v[202:205], v160 offset:5120
	ds_read_b128 v[206:209], v160 offset:6144
	ds_read_b128 v[210:213], v160 offset:7168
	global_load_lds_dwordx4 v[214:215], off
	v_lshl_add_u64 v[214:215], s[66:67], 0, v[144:145]
	s_add_i32 m0, s83, 0xe000
	s_nop 0
	global_load_lds_dwordx4 v[214:215], off
	s_waitcnt vmcnt(8)
	s_waitcnt lgkmcnt(0)
	s_barrier
	s_setprio 1
	s_waitcnt lgkmcnt(0)
	v_mfma_f32_16x16x32_bf16 v[126:129], v[146:149], v[182:185], v[126:129]
	v_mfma_f32_16x16x32_bf16 v[118:121], v[154:157], v[182:185], v[118:121]
	v_mfma_f32_16x16x32_bf16 v[102:105], v[154:157], v[190:193], v[102:105]
	v_mfma_f32_16x16x32_bf16 v[110:113], v[146:149], v[190:193], v[110:113]
	v_mfma_f32_16x16x32_bf16 v[94:97], v[146:149], v[198:201], v[94:97]
	v_mfma_f32_16x16x32_bf16 v[86:89], v[154:157], v[198:201], v[86:89]
	v_mfma_f32_16x16x32_bf16 v[70:73], v[154:157], v[206:209], v[70:73]
	v_mfma_f32_16x16x32_bf16 v[78:81], v[146:149], v[206:209], v[78:81]
	v_mfma_f32_16x16x32_bf16 v[126:129], v[150:153], v[186:189], v[126:129]
	v_mfma_f32_16x16x32_bf16 v[118:121], v[162:165], v[186:189], v[118:121]
	v_mfma_f32_16x16x32_bf16 v[102:105], v[162:165], v[194:197], v[102:105]
	v_mfma_f32_16x16x32_bf16 v[110:113], v[150:153], v[194:197], v[110:113]
	v_mfma_f32_16x16x32_bf16 v[94:97], v[150:153], v[202:205], v[94:97]
	v_mfma_f32_16x16x32_bf16 v[86:89], v[162:165], v[202:205], v[86:89]
	v_mfma_f32_16x16x32_bf16 v[70:73], v[162:165], v[210:213], v[70:73]
	v_mfma_f32_16x16x32_bf16 v[78:81], v[150:153], v[210:213], v[78:81]
	s_setprio 0
	s_setprio 1
	v_mfma_f32_16x16x32_bf16 v[122:125], v[166:169], v[182:185], v[122:125]
	v_mfma_f32_16x16x32_bf16 v[114:117], v[174:177], v[182:185], v[114:117]
	v_mfma_f32_16x16x32_bf16 v[98:101], v[174:177], v[190:193], v[98:101]
	v_mfma_f32_16x16x32_bf16 v[106:109], v[166:169], v[190:193], v[106:109]
	v_mfma_f32_16x16x32_bf16 v[90:93], v[166:169], v[198:201], v[90:93]
	v_mfma_f32_16x16x32_bf16 v[82:85], v[174:177], v[198:201], v[82:85]
	v_mfma_f32_16x16x32_bf16 v[66:69], v[174:177], v[206:209], v[66:69]
	v_mfma_f32_16x16x32_bf16 v[74:77], v[166:169], v[206:209], v[74:77]
	v_mfma_f32_16x16x32_bf16 v[122:125], v[170:173], v[186:189], v[122:125]
	v_mfma_f32_16x16x32_bf16 v[114:117], v[178:181], v[186:189], v[114:117]
	v_mfma_f32_16x16x32_bf16 v[98:101], v[178:181], v[194:197], v[98:101]
	v_mfma_f32_16x16x32_bf16 v[106:109], v[170:173], v[194:197], v[106:109]
	v_mfma_f32_16x16x32_bf16 v[90:93], v[170:173], v[202:205], v[90:93]
	v_mfma_f32_16x16x32_bf16 v[82:85], v[178:181], v[202:205], v[82:85]
	v_mfma_f32_16x16x32_bf16 v[66:69], v[178:181], v[210:213], v[66:69]
	v_mfma_f32_16x16x32_bf16 v[74:77], v[170:173], v[210:213], v[74:77]
	s_setprio 0
	s_barrier
	s_add_i32 s61, s90, s82
	v_lshl_add_u64 v[214:215], s[68:69], 0, v[132:133]
	s_mov_b32 m0, s61
	ds_read_b128 v[182:185], v160 offset:16384
	ds_read_b128 v[186:189], v160 offset:17408
	ds_read_b128 v[190:193], v160 offset:18432
	ds_read_b128 v[194:197], v160 offset:19456
	ds_read_b128 v[198:201], v160 offset:20480
	ds_read_b128 v[202:205], v160 offset:21504
	ds_read_b128 v[206:209], v160 offset:22528
	ds_read_b128 v[210:213], v160 offset:23552
	global_load_lds_dwordx4 v[214:215], off
	s_add_i32 m0, s61, 0x2000
	s_add_u32 s72, s68, 0x100000
	v_lshl_add_u64 v[216:217], s[68:69], 0, v[136:137]
	s_addc_u32 s73, s69, 0
	s_add_i32 s61, s91, s82
	global_load_lds_dwordx4 v[216:217], off
	v_lshl_add_u64 v[218:219], s[72:73], 0, v[132:133]
	s_mov_b32 m0, s61
	v_lshl_add_u64 v[220:221], s[70:71], 0, v[134:135]
	global_load_lds_dwordx4 v[218:219], off
	v_lshl_add_u64 v[218:219], s[72:73], 0, v[136:137]
	s_add_i32 m0, s61, 0x2000
	s_nop 0
	global_load_lds_dwordx4 v[218:219], off
	v_lshl_add_u64 v[218:219], s[70:71], 0, v[130:131]
	s_mov_b32 m0, s83
	s_nop 0
	global_load_lds_dwordx4 v[218:219], off
	s_mov_b32 m0, s84
	s_nop 0
	global_load_lds_dwordx4 v[220:221], off
	s_waitcnt vmcnt(8)
	s_waitcnt lgkmcnt(0)
	s_barrier
; #define PG8_STAGE(bufoff, gbase, voff) do { _Pragma("unroll") for (int _i = 0; _i < 2; ++_i) \
;         __builtin_amdgcn_global_load_lds((const unsigned*)((const char*)(gbase) + (voff)[_i]), (LAS unsigned*)(lds + (bufoff) + ldsw + _i * 8192), 16, 0, 0); } while (0)
; #define PG8_LDA(dst, b, h) do { _Pragma("unroll") for (int m = 0; m < 4; ++m) _Pragma("unroll") for (int k = 0; k < 2; ++k) dst[m][k] = *(const LAS bf16x8*)(lds + PG8_SA(b, h) + aoff + m * 2048 + k * 1024); } while (0)
; #define PG8_LDB(dst, b, h) do { _Pragma("unroll") for (int n = 0; n < 2; ++n) _Pragma("unroll") for (int k = 0; k < 2; ++k) dst[n][k] = *(const LAS bf16x8*)(lds + PG8_SB(b, h) + boff + n * 2048 + k * 1024); } while (0)
; #define PG8_MMA(ai, bj, At, Bt) do { __builtin_amdgcn_s_setprio(1); _Pragma("unroll") for (int m = 0; m < 4; ++m) _Pragma("unroll") for (int n = 0; n < 2; ++n) _Pragma("unroll") for (int k = 0; k < 2; ++k) \
;         acc[ai][bj][m][n] = __builtin_amdgcn_mfma_f32_16x16x32_bf16(Bt[n][k], At[m][k], acc[ai][bj][m][n], 0, 0, 0); __builtin_amdgcn_s_setprio(0); } while (0)
; #define PG8_WAIT_V(n) asm volatile("s_waitcnt vmcnt(" #n ")" ::: "memory")
; #define PG8_WAIT_L(n) asm volatile("s_waitcnt lgkmcnt(" #n ")" ::: "memory")
; #define PG8_BAR __builtin_amdgcn_s_barrier()
; #define PG8_SCHED __builtin_amdgcn_sched_barrier(0)
; template <class Epi, class Sched, bool ALIGN_EPI, bool SP2, bool BPRE = false>
; __device__ __forceinline__ void gemm_phase(LAS unsigned char* lds, const int pitchA, const int pitchB, const Sched& S, const Epi& E) {
;     ...
;             PG8_WAIT_V(8); PG8_WAIT_L(0); PG8_BAR; PG8_MMA(1, 0, At, B0); PG8_MMA(1, 1, At, B1); PG8_BAR; PG8_SCHED;
;             PG8_LDB(B0, 1, 0); PG8_LDB(B1, 1, 1); PG8_SCHED; PG8_LDA(At, 1, 0); PG8_STAGE(PG8_SA(0, 1), a2 + hstepA, voffA);
;             PG8_WAIT_V(8); PG8_WAIT_L(0); PG8_BAR; PG8_MMA(0, 0, At, B0); PG8_MMA(0, 1, At, B1); PG8_BAR; PG8_SCHED;
	s_setprio 1
	s_waitcnt lgkmcnt(0)
	v_mfma_f32_16x16x32_bf16 v[62:65], v[146:149], v[182:185], v[62:65]
	v_mfma_f32_16x16x32_bf16 v[54:57], v[154:157], v[182:185], v[54:57]
	v_mfma_f32_16x16x32_bf16 v[38:41], v[154:157], v[190:193], v[38:41]
	v_mfma_f32_16x16x32_bf16 v[46:49], v[146:149], v[190:193], v[46:49]
	v_mfma_f32_16x16x32_bf16 v[30:33], v[146:149], v[198:201], v[30:33]
	v_mfma_f32_16x16x32_bf16 v[22:25], v[154:157], v[198:201], v[22:25]
	v_mfma_f32_16x16x32_bf16 v[6:9], v[154:157], v[206:209], v[6:9]
	v_mfma_f32_16x16x32_bf16 v[14:17], v[146:149], v[206:209], v[14:17]
	v_mfma_f32_16x16x32_bf16 v[62:65], v[150:153], v[186:189], v[62:65]
	v_mfma_f32_16x16x32_bf16 v[54:57], v[162:165], v[186:189], v[54:57]
	v_mfma_f32_16x16x32_bf16 v[38:41], v[162:165], v[194:197], v[38:41]
	v_mfma_f32_16x16x32_bf16 v[46:49], v[150:153], v[194:197], v[46:49]
	v_mfma_f32_16x16x32_bf16 v[30:33], v[150:153], v[202:205], v[30:33]
	v_mfma_f32_16x16x32_bf16 v[22:25], v[162:165], v[202:205], v[22:25]
	v_mfma_f32_16x16x32_bf16 v[6:9], v[162:165], v[210:213], v[6:9]
	v_mfma_f32_16x16x32_bf16 v[14:17], v[150:153], v[210:213], v[14:17]
	s_setprio 0
	s_setprio 1
	v_mfma_f32_16x16x32_bf16 v[58:61], v[166:169], v[182:185], v[58:61]
	v_mfma_f32_16x16x32_bf16 v[50:53], v[174:177], v[182:185], v[50:53]
	v_mfma_f32_16x16x32_bf16 v[34:37], v[174:177], v[190:193], v[34:37]
	v_mfma_f32_16x16x32_bf16 v[42:45], v[166:169], v[190:193], v[42:45]
	v_mfma_f32_16x16x32_bf16 v[26:29], v[166:169], v[198:201], v[26:29]
	v_mfma_f32_16x16x32_bf16 v[18:21], v[174:177], v[198:201], v[18:21]
	v_mfma_f32_16x16x32_bf16 v[2:5], v[174:177], v[206:209], v[2:5]
	v_mfma_f32_16x16x32_bf16 v[10:13], v[166:169], v[206:209], v[10:13]
	v_mfma_f32_16x16x32_bf16 v[58:61], v[170:173], v[186:189], v[58:61]
	v_mfma_f32_16x16x32_bf16 v[50:53], v[178:181], v[186:189], v[50:53]
	v_mfma_f32_16x16x32_bf16 v[34:37], v[178:181], v[194:197], v[34:37]
	v_mfma_f32_16x16x32_bf16 v[42:45], v[170:173], v[194:197], v[42:45]
	v_mfma_f32_16x16x32_bf16 v[26:29], v[170:173], v[202:205], v[26:29]
	v_mfma_f32_16x16x32_bf16 v[18:21], v[178:181], v[202:205], v[18:21]
	v_mfma_f32_16x16x32_bf16 v[2:5], v[178:181], v[210:213], v[2:5]
	v_mfma_f32_16x16x32_bf16 v[10:13], v[170:173], v[210:213], v[10:13]
	s_setprio 0
	s_barrier
	s_add_i32 s61, 0, 0x18000
	v_add_u32_e32 v138, s61, v141
	s_add_i32 s63, 0, 0x1c000
	ds_read_b128 v[146:149], v138
	ds_read_b128 v[150:153], v138 offset:1024
	ds_read_b128 v[154:157], v138 offset:2048
	ds_read_b128 v[162:165], v138 offset:3072
	v_add_u32_e32 v138, s63, v141
	ds_read_b128 v[166:169], v138
	ds_read_b128 v[170:173], v138 offset:1024
	ds_read_b128 v[174:177], v138 offset:2048
	ds_read_b128 v[178:181], v138 offset:3072
	s_add_u32 s70, s70, 0x100000
	s_addc_u32 s71, s71, 0
	s_mov_b32 m0, s85
	v_lshl_add_u64 v[222:223], s[70:71], 0, v[130:131]
	ds_read_b128 v[182:185], v160 offset:32768
	ds_read_b128 v[186:189], v160 offset:33792
	ds_read_b128 v[190:193], v160 offset:34816
	ds_read_b128 v[194:197], v160 offset:35840
	ds_read_b128 v[198:201], v160 offset:36864
	ds_read_b128 v[202:205], v160 offset:37888
	ds_read_b128 v[206:209], v160 offset:38912
	ds_read_b128 v[210:213], v160 offset:39936
	global_load_lds_dwordx4 v[222:223], off
	v_lshl_add_u64 v[222:223], s[70:71], 0, v[134:135]
	s_mov_b32 m0, s86
	s_nop 0
	global_load_lds_dwordx4 v[222:223], off
	s_waitcnt vmcnt(8)
	s_waitcnt lgkmcnt(0)
	s_barrier
	s_setprio 1
	s_waitcnt lgkmcnt(0)
	v_mfma_f32_16x16x32_bf16 v[126:129], v[146:149], v[182:185], v[126:129]
	v_mfma_f32_16x16x32_bf16 v[118:121], v[154:157], v[182:185], v[118:121]
	v_mfma_f32_16x16x32_bf16 v[102:105], v[154:157], v[190:193], v[102:105]
	v_mfma_f32_16x16x32_bf16 v[110:113], v[146:149], v[190:193], v[110:113]
	v_mfma_f32_16x16x32_bf16 v[94:97], v[146:149], v[198:201], v[94:97]
	v_mfma_f32_16x16x32_bf16 v[86:89], v[154:157], v[198:201], v[86:89]
	v_mfma_f32_16x16x32_bf16 v[70:73], v[154:157], v[206:209], v[70:73]
	v_mfma_f32_16x16x32_bf16 v[78:81], v[146:149], v[206:209], v[78:81]
	v_mfma_f32_16x16x32_bf16 v[126:129], v[150:153], v[186:189], v[126:129]
	v_mfma_f32_16x16x32_bf16 v[118:121], v[162:165], v[186:189], v[118:121]
	v_mfma_f32_16x16x32_bf16 v[102:105], v[162:165], v[194:197], v[102:105]
	v_mfma_f32_16x16x32_bf16 v[110:113], v[150:153], v[194:197], v[110:113]
	v_mfma_f32_16x16x32_bf16 v[94:97], v[150:153], v[202:205], v[94:97]
	v_mfma_f32_16x16x32_bf16 v[86:89], v[162:165], v[202:205], v[86:89]
	v_mfma_f32_16x16x32_bf16 v[70:73], v[162:165], v[210:213], v[70:73]
	v_mfma_f32_16x16x32_bf16 v[78:81], v[150:153], v[210:213], v[78:81]
	s_setprio 0
	s_setprio 1
	v_mfma_f32_16x16x32_bf16 v[122:125], v[166:169], v[182:185], v[122:125]
	v_mfma_f32_16x16x32_bf16 v[114:117], v[174:177], v[182:185], v[114:117]
	v_mfma_f32_16x16x32_bf16 v[98:101], v[174:177], v[190:193], v[98:101]
	v_mfma_f32_16x16x32_bf16 v[106:109], v[166:169], v[190:193], v[106:109]
	v_mfma_f32_16x16x32_bf16 v[90:93], v[166:169], v[198:201], v[90:93]
	v_mfma_f32_16x16x32_bf16 v[82:85], v[174:177], v[198:201], v[82:85]
	v_mfma_f32_16x16x32_bf16 v[66:69], v[174:177], v[206:209], v[66:69]
	v_mfma_f32_16x16x32_bf16 v[74:77], v[166:169], v[206:209], v[74:77]
	v_mfma_f32_16x16x32_bf16 v[122:125], v[170:173], v[186:189], v[122:125]
	v_mfma_f32_16x16x32_bf16 v[114:117], v[178:181], v[186:189], v[114:117]
	v_mfma_f32_16x16x32_bf16 v[98:101], v[178:181], v[194:197], v[98:101]
	v_mfma_f32_16x16x32_bf16 v[106:109], v[170:173], v[194:197], v[106:109]
	v_mfma_f32_16x16x32_bf16 v[90:93], v[170:173], v[202:205], v[90:93]
	v_mfma_f32_16x16x32_bf16 v[82:85], v[178:181], v[202:205], v[82:85]
	v_mfma_f32_16x16x32_bf16 v[66:69], v[178:181], v[210:213], v[66:69]
	v_mfma_f32_16x16x32_bf16 v[74:77], v[170:173], v[210:213], v[74:77]
	s_setprio 0
	s_barrier
; #define PG8_STAGE(bufoff, gbase, voff) do { _Pragma("unroll") for (int _i = 0; _i < 2; ++_i) \
;         __builtin_amdgcn_global_load_lds((const unsigned*)((const char*)(gbase) + (voff)[_i]), (LAS unsigned*)(lds + (bufoff) + ldsw + _i * 8192), 16, 0, 0); } while (0)
; #define PG8_LDA(dst, b, h) do { _Pragma("unroll") for (int m = 0; m < 4; ++m) _Pragma("unroll") for (int k = 0; k < 2; ++k) dst[m][k] = *(const LAS bf16x8*)(lds + PG8_SA(b, h) + aoff + m * 2048 + k * 1024); } while (0)
; #define PG8_MMA(ai, bj, At, Bt) do { __builtin_amdgcn_s_setprio(1); _Pragma("unroll") for (int m = 0; m < 4; ++m) _Pragma("unroll") for (int n = 0; n < 2; ++n) _Pragma("unroll") for (int k = 0; k < 2; ++k) \
;         acc[ai][bj][m][n] = __builtin_amdgcn_mfma_f32_16x16x32_bf16(Bt[n][k], At[m][k], acc[ai][bj][m][n], 0, 0, 0); __builtin_amdgcn_s_setprio(0); } while (0)
; #define PG8_WAIT_V(n) asm volatile("s_waitcnt vmcnt(" #n ")" ::: "memory")
; #define PG8_WAIT_L(n) asm volatile("s_waitcnt lgkmcnt(" #n ")" ::: "memory")
; #define PG8_BAR __builtin_amdgcn_s_barrier()
; #define PG8_SCHED __builtin_amdgcn_sched_barrier(0)
; template <class Epi, class Sched, bool ALIGN_EPI, bool SP2, bool BPRE = false>
; __device__ __forceinline__ void gemm_phase(LAS unsigned char* lds, const int pitchA, const int pitchB, const Sched& S, const Epi& E) {
;     ...
;         for (int t = 0; t < nt; t += 2) {
;     ...
;             PG8_LDA(At, 1, 1); PG8_STAGE(PG8_SB(1, 0), b3, voffB); PG8_STAGE(PG8_SB(1, 1), b3 + hstepB, voffB); PG8_STAGE(PG8_SA(1, 0), a3, voffA);
;             PG8_WAIT_V(8); PG8_WAIT_L(0); PG8_BAR; PG8_MMA(1, 0, At, B0); PG8_MMA(1, 1, At, B1); PG8_BAR; PG8_SCHED;
	s_add_i32 s61, s61, s82
	v_lshl_add_u64 v[214:215], v[214:215], 0, s[50:51]
	s_mov_b32 m0, s61
	ds_read_b128 v[182:185], v160 offset:49152
	ds_read_b128 v[186:189], v160 offset:50176
	ds_read_b128 v[190:193], v160 offset:51200
	ds_read_b128 v[194:197], v160 offset:52224
	ds_read_b128 v[198:201], v160 offset:53248
	ds_read_b128 v[202:205], v160 offset:54272
	ds_read_b128 v[206:209], v160 offset:55296
	ds_read_b128 v[210:213], v160 offset:56320
	global_load_lds_dwordx4 v[214:215], off
	s_add_i32 m0, s61, 0x2000
	s_add_u32 s68, s68, 0x100080
	v_lshl_add_u64 v[214:215], v[216:217], 0, s[50:51]
	s_addc_u32 s69, s69, 0
	s_add_i32 s61, s63, s82
	global_load_lds_dwordx4 v[214:215], off
	v_lshl_add_u64 v[214:215], s[68:69], 0, v[132:133]
	s_mov_b32 m0, s61
	s_nop 0
	global_load_lds_dwordx4 v[214:215], off
	v_lshl_add_u64 v[214:215], s[68:69], 0, v[136:137]
	s_add_i32 m0, s61, 0x2000
	s_nop 0
	global_load_lds_dwordx4 v[214:215], off
	v_lshl_add_u64 v[214:215], v[218:219], 0, s[50:51]
	s_mov_b32 m0, s88
	s_nop 0
	global_load_lds_dwordx4 v[214:215], off
	v_lshl_add_u64 v[214:215], v[220:221], 0, s[50:51]
	s_mov_b32 m0, s89
	s_nop 0
	global_load_lds_dwordx4 v[214:215], off
	s_waitcnt vmcnt(8)
	s_waitcnt lgkmcnt(0)
	s_barrier
	s_setprio 1
	s_waitcnt lgkmcnt(0)
	v_mfma_f32_16x16x32_bf16 v[62:65], v[146:149], v[182:185], v[62:65]
	v_mfma_f32_16x16x32_bf16 v[54:57], v[154:157], v[182:185], v[54:57]
	v_mfma_f32_16x16x32_bf16 v[38:41], v[154:157], v[190:193], v[38:41]
	v_mfma_f32_16x16x32_bf16 v[46:49], v[146:149], v[190:193], v[46:49]
	v_mfma_f32_16x16x32_bf16 v[30:33], v[146:149], v[198:201], v[30:33]
	v_mfma_f32_16x16x32_bf16 v[22:25], v[154:157], v[198:201], v[22:25]
	v_mfma_f32_16x16x32_bf16 v[6:9], v[154:157], v[206:209], v[6:9]
	v_mfma_f32_16x16x32_bf16 v[14:17], v[146:149], v[206:209], v[14:17]
	v_mfma_f32_16x16x32_bf16 v[62:65], v[150:153], v[186:189], v[62:65]
	v_mfma_f32_16x16x32_bf16 v[54:57], v[162:165], v[186:189], v[54:57]
	v_mfma_f32_16x16x32_bf16 v[38:41], v[162:165], v[194:197], v[38:41]
	v_mfma_f32_16x16x32_bf16 v[46:49], v[150:153], v[194:197], v[46:49]
	v_mfma_f32_16x16x32_bf16 v[30:33], v[150:153], v[202:205], v[30:33]
	v_mfma_f32_16x16x32_bf16 v[22:25], v[162:165], v[202:205], v[22:25]
	v_mfma_f32_16x16x32_bf16 v[6:9], v[162:165], v[210:213], v[6:9]
	v_mfma_f32_16x16x32_bf16 v[14:17], v[150:153], v[210:213], v[14:17]
	s_setprio 0
	s_setprio 1
	v_mfma_f32_16x16x32_bf16 v[58:61], v[166:169], v[182:185], v[58:61]
	v_mfma_f32_16x16x32_bf16 v[50:53], v[174:177], v[182:185], v[50:53]
	v_mfma_f32_16x16x32_bf16 v[34:37], v[174:177], v[190:193], v[34:37]
	v_mfma_f32_16x16x32_bf16 v[42:45], v[166:169], v[190:193], v[42:45]
	v_mfma_f32_16x16x32_bf16 v[26:29], v[166:169], v[198:201], v[26:29]
	v_mfma_f32_16x16x32_bf16 v[18:21], v[174:177], v[198:201], v[18:21]
	v_mfma_f32_16x16x32_bf16 v[2:5], v[174:177], v[206:209], v[2:5]
	v_mfma_f32_16x16x32_bf16 v[10:13], v[166:169], v[206:209], v[10:13]
	v_mfma_f32_16x16x32_bf16 v[58:61], v[170:173], v[186:189], v[58:61]
	v_mfma_f32_16x16x32_bf16 v[50:53], v[178:181], v[186:189], v[50:53]
	v_mfma_f32_16x16x32_bf16 v[34:37], v[178:181], v[194:197], v[34:37]
	v_mfma_f32_16x16x32_bf16 v[42:45], v[170:173], v[194:197], v[42:45]
	v_mfma_f32_16x16x32_bf16 v[26:29], v[170:173], v[202:205], v[26:29]
	v_mfma_f32_16x16x32_bf16 v[18:21], v[178:181], v[202:205], v[18:21]
	v_mfma_f32_16x16x32_bf16 v[2:5], v[178:181], v[210:213], v[2:5]
	v_mfma_f32_16x16x32_bf16 v[10:13], v[170:173], v[210:213], v[10:13]
	s_setprio 0
	s_barrier
	s_add_i32 s59, s59, 2
	s_add_u32 s66, s66, 0x100
	s_addc_u32 s67, s67, 0
	s_add_u32 s5, s5, 0x100
	s_addc_u32 s6, s6, 0
	s_cmp_gt_u32 s59, 61
	s_cbranch_scc0 .LBB0_157
	s_and_b64 vcc, exec, s[52:53]
	s_cbranch_vccz .LBB0_160
	s_barrier

; #define PG8_STAGE(bufoff, gbase, voff) do { _Pragma("unroll") for (int _i = 0; _i < 2; ++_i) \
;         __builtin_amdgcn_global_load_lds((const unsigned*)((const char*)(gbase) + (voff)[_i]), (LAS unsigned*)(lds + (bufoff) + ldsw + _i * 8192), 16, 0, 0); } while (0)
; #define PG8_LDA(dst, b, h) do { _Pragma("unroll") for (int m = 0; m < 4; ++m) _Pragma("unroll") for (int k = 0; k < 2; ++k) dst[m][k] = *(const LAS bf16x8*)(lds + PG8_SA(b, h) + aoff + m * 2048 + k * 1024); } while (0)
; #define PG8_LDB(dst, b, h) do { _Pragma("unroll") for (int n = 0; n < 2; ++n) _Pragma("unroll") for (int k = 0; k < 2; ++k) dst[n][k] = *(const LAS bf16x8*)(lds + PG8_SB(b, h) + boff + n * 2048 + k * 1024); } while (0)
; #define PG8_MMA(ai, bj, At, Bt) do { __builtin_amdgcn_s_setprio(1); _Pragma("unroll") for (int m = 0; m < 4; ++m) _Pragma("unroll") for (int n = 0; n < 2; ++n) _Pragma("unroll") for (int k = 0; k < 2; ++k) \
;         acc[ai][bj][m][n] = __builtin_amdgcn_mfma_f32_16x16x32_bf16(Bt[n][k], At[m][k], acc[ai][bj][m][n], 0, 0, 0); __builtin_amdgcn_s_setprio(0); } while (0)
; #define PG8_WAIT_V(n) asm volatile("s_waitcnt vmcnt(" #n ")" ::: "memory")
; #define PG8_WAIT_L(n) asm volatile("s_waitcnt lgkmcnt(" #n ")" ::: "memory")
; #define PG8_BAR __builtin_amdgcn_s_barrier()
; #define PG8_SCHED __builtin_amdgcn_sched_barrier(0)
; template <class Epi, class Sched, bool ALIGN_EPI, bool SP2, bool BPRE = false>
; __device__ __forceinline__ void gemm_phase(LAS unsigned char* lds, const int pitchA, const int pitchB, const Sched& S, const Epi& E) {
;     ...
;             PG8_LDB(B0, 0, 0); PG8_LDB(B1, 0, 1); PG8_SCHED; PG8_LDA(At, 0, 0); PG8_STAGE(PG8_SA(1, 1), a1 + hstepA, voffA);
;             PG8_WAIT_V(8); PG8_WAIT_L(0); PG8_BAR; PG8_MMA(0, 0, At, B0); PG8_MMA(0, 1, At, B1); PG8_BAR; PG8_SCHED;
;             PG8_LDA(At, 0, 1); PG8_STAGE(PG8_SB(0, 0), b2, voffB); PG8_STAGE(PG8_SB(0, 1), b2 + hstepB, voffB); PG8_STAGE(PG8_SA(0, 0), a2, voffA);
;             PG8_WAIT_V(8); PG8_WAIT_L(0); PG8_BAR; PG8_MMA(1, 0, At, B0); PG8_MMA(1, 1, At, B1); PG8_BAR; PG8_SCHED;
.LBB0_765:
	ds_read_b128 v[150:153], v147
	ds_read_b128 v[154:157], v147 offset:1024
	ds_read_b128 v[158:161], v147 offset:2048
	ds_read_b128 v[162:165], v147 offset:3072
	ds_read_b128 v[166:169], v148
	ds_read_b128 v[170:173], v148 offset:1024
	ds_read_b128 v[174:177], v148 offset:2048
	ds_read_b128 v[178:181], v148 offset:3072
	s_add_i32 s72, s40, 2
	s_add_u32 s41, s38, 0xfff00080
	s_addc_u32 s42, s39, -1
	s_cmp_eq_u32 s69, s40
	s_cselect_b32 s40, s68, s70
	s_cselect_b32 s43, s6, s42
	s_cselect_b32 s42, s66, s41
	s_cselect_b32 s41, s67, s71
	v_lshl_add_u64 v[142:143], s[38:39], 0, v[138:139]
	s_add_i32 m0, s44, 0xc000
	ds_read_b128 v[182:185], v149
	ds_read_b128 v[186:189], v149 offset:1024
	ds_read_b128 v[190:193], v149 offset:2048
	ds_read_b128 v[194:197], v149 offset:3072
	ds_read_b128 v[198:201], v149 offset:4096
	ds_read_b128 v[202:205], v149 offset:5120
	ds_read_b128 v[206:209], v149 offset:6144
	ds_read_b128 v[210:213], v149 offset:7168
	global_load_lds_dwordx4 v[142:143], off
	v_lshl_add_u64 v[142:143], s[38:39], 0, v[140:141]
	s_add_i32 m0, s44, 0xe000
	s_nop 0
	global_load_lds_dwordx4 v[142:143], off
	s_waitcnt vmcnt(8)
	s_waitcnt lgkmcnt(0)
	s_barrier
	s_setprio 1
	s_waitcnt lgkmcnt(0)
	v_mfma_f32_16x16x32_bf16 v[126:129], v[150:153], v[182:185], v[126:129]
	v_mfma_f32_16x16x32_bf16 v[122:125], v[158:161], v[182:185], v[122:125]
	v_mfma_f32_16x16x32_bf16 v[110:113], v[158:161], v[190:193], v[110:113]
	v_mfma_f32_16x16x32_bf16 v[118:121], v[150:153], v[190:193], v[118:121]
	v_mfma_f32_16x16x32_bf16 v[102:105], v[150:153], v[198:201], v[102:105]
	v_mfma_f32_16x16x32_bf16 v[94:97], v[158:161], v[198:201], v[94:97]
	v_mfma_f32_16x16x32_bf16 v[78:81], v[158:161], v[206:209], v[78:81]
	v_mfma_f32_16x16x32_bf16 v[86:89], v[150:153], v[206:209], v[86:89]
	v_mfma_f32_16x16x32_bf16 v[126:129], v[154:157], v[186:189], v[126:129]
	v_mfma_f32_16x16x32_bf16 v[122:125], v[162:165], v[186:189], v[122:125]
	v_mfma_f32_16x16x32_bf16 v[110:113], v[162:165], v[194:197], v[110:113]
	v_mfma_f32_16x16x32_bf16 v[118:121], v[154:157], v[194:197], v[118:121]
	v_mfma_f32_16x16x32_bf16 v[102:105], v[154:157], v[202:205], v[102:105]
	v_mfma_f32_16x16x32_bf16 v[94:97], v[162:165], v[202:205], v[94:97]
	v_mfma_f32_16x16x32_bf16 v[78:81], v[162:165], v[210:213], v[78:81]
	v_mfma_f32_16x16x32_bf16 v[86:89], v[154:157], v[210:213], v[86:89]
	s_setprio 0
	s_setprio 1
	v_mfma_f32_16x16x32_bf16 v[114:117], v[166:169], v[182:185], v[114:117]
	v_mfma_f32_16x16x32_bf16 v[106:109], v[174:177], v[182:185], v[106:109]
	v_mfma_f32_16x16x32_bf16 v[90:93], v[174:177], v[190:193], v[90:93]
	v_mfma_f32_16x16x32_bf16 v[98:101], v[166:169], v[190:193], v[98:101]
	v_mfma_f32_16x16x32_bf16 v[82:85], v[166:169], v[198:201], v[82:85]
	v_mfma_f32_16x16x32_bf16 v[74:77], v[174:177], v[198:201], v[74:77]
	v_mfma_f32_16x16x32_bf16 v[66:69], v[174:177], v[206:209], v[66:69]
	v_mfma_f32_16x16x32_bf16 v[70:73], v[166:169], v[206:209], v[70:73]
	v_mfma_f32_16x16x32_bf16 v[114:117], v[170:173], v[186:189], v[114:117]
	v_mfma_f32_16x16x32_bf16 v[106:109], v[178:181], v[186:189], v[106:109]
	v_mfma_f32_16x16x32_bf16 v[90:93], v[178:181], v[194:197], v[90:93]
	v_mfma_f32_16x16x32_bf16 v[98:101], v[170:173], v[194:197], v[98:101]
	v_mfma_f32_16x16x32_bf16 v[82:85], v[170:173], v[202:205], v[82:85]
	v_mfma_f32_16x16x32_bf16 v[74:77], v[178:181], v[202:205], v[74:77]
	v_mfma_f32_16x16x32_bf16 v[66:69], v[178:181], v[210:213], v[66:69]
	v_mfma_f32_16x16x32_bf16 v[70:73], v[170:173], v[210:213], v[70:73]
	s_setprio 0
	s_barrier
	s_add_i32 s73, s52, s37
	v_lshl_add_u64 v[142:143], s[40:41], 0, v[134:135]
	s_mov_b32 m0, s73
	ds_read_b128 v[182:185], v149 offset:16384
	ds_read_b128 v[186:189], v149 offset:17408
	ds_read_b128 v[190:193], v149 offset:18432
	ds_read_b128 v[194:197], v149 offset:19456
	ds_read_b128 v[198:201], v149 offset:20480
	ds_read_b128 v[202:205], v149 offset:21504
	ds_read_b128 v[206:209], v149 offset:22528
	ds_read_b128 v[210:213], v149 offset:23552
	global_load_lds_dwordx4 v[142:143], off
	s_add_i32 m0, s73, 0x2000
	s_add_u32 s74, s40, 0x100000
	v_lshl_add_u64 v[214:215], s[40:41], 0, v[136:137]
	s_addc_u32 s75, s41, 0
	s_add_i32 s73, s53, s37
	global_load_lds_dwordx4 v[214:215], off
	v_lshl_add_u64 v[216:217], s[74:75], 0, v[134:135]
	s_mov_b32 m0, s73
	v_lshl_add_u64 v[218:219], s[42:43], 0, v[132:133]
	global_load_lds_dwordx4 v[216:217], off
	v_lshl_add_u64 v[216:217], s[74:75], 0, v[136:137]
	s_add_i32 m0, s73, 0x2000
	s_nop 0
	global_load_lds_dwordx4 v[216:217], off
	v_lshl_add_u64 v[216:217], s[42:43], 0, v[130:131]
	s_mov_b32 m0, s44
	s_nop 0
	global_load_lds_dwordx4 v[216:217], off
	s_mov_b32 m0, s45
	s_nop 0
	global_load_lds_dwordx4 v[218:219], off
	s_waitcnt vmcnt(8)
	s_waitcnt lgkmcnt(0)
	s_barrier
; #define PG8_STAGE(bufoff, gbase, voff) do { _Pragma("unroll") for (int _i = 0; _i < 2; ++_i) \
;         __builtin_amdgcn_global_load_lds((const unsigned*)((const char*)(gbase) + (voff)[_i]), (LAS unsigned*)(lds + (bufoff) + ldsw + _i * 8192), 16, 0, 0); } while (0)
; #define PG8_LDA(dst, b, h) do { _Pragma("unroll") for (int m = 0; m < 4; ++m) _Pragma("unroll") for (int k = 0; k < 2; ++k) dst[m][k] = *(const LAS bf16x8*)(lds + PG8_SA(b, h) + aoff + m * 2048 + k * 1024); } while (0)
; #define PG8_LDB(dst, b, h) do { _Pragma("unroll") for (int n = 0; n < 2; ++n) _Pragma("unroll") for (int k = 0; k < 2; ++k) dst[n][k] = *(const LAS bf16x8*)(lds + PG8_SB(b, h) + boff + n * 2048 + k * 1024); } while (0)
; #define PG8_MMA(ai, bj, At, Bt) do { __builtin_amdgcn_s_setprio(1); _Pragma("unroll") for (int m = 0; m < 4; ++m) _Pragma("unroll") for (int n = 0; n < 2; ++n) _Pragma("unroll") for (int k = 0; k < 2; ++k) \
;         acc[ai][bj][m][n] = __builtin_amdgcn_mfma_f32_16x16x32_bf16(Bt[n][k], At[m][k], acc[ai][bj][m][n], 0, 0, 0); __builtin_amdgcn_s_setprio(0); } while (0)
; #define PG8_WAIT_V(n) asm volatile("s_waitcnt vmcnt(" #n ")" ::: "memory")
; #define PG8_WAIT_L(n) asm volatile("s_waitcnt lgkmcnt(" #n ")" ::: "memory")
; #define PG8_BAR __builtin_amdgcn_s_barrier()
; #define PG8_SCHED __builtin_amdgcn_sched_barrier(0)
; template <class Epi, class Sched, bool ALIGN_EPI, bool SP2, bool BPRE = false>
; __device__ __forceinline__ void gemm_phase(LAS unsigned char* lds, const int pitchA, const int pitchB, const Sched& S, const Epi& E) {
;     ...
;             PG8_WAIT_V(8); PG8_WAIT_L(0); PG8_BAR; PG8_MMA(1, 0, At, B0); PG8_MMA(1, 1, At, B1); PG8_BAR; PG8_SCHED;
;             PG8_LDB(B0, 1, 0); PG8_LDB(B1, 1, 1); PG8_SCHED; PG8_LDA(At, 1, 0); PG8_STAGE(PG8_SA(0, 1), a2 + hstepA, voffA);
;             PG8_WAIT_V(8); PG8_WAIT_L(0); PG8_BAR; PG8_MMA(0, 0, At, B0); PG8_MMA(0, 1, At, B1); PG8_BAR; PG8_SCHED;
	s_setprio 1
	s_waitcnt lgkmcnt(0)
	v_mfma_f32_16x16x32_bf16 v[62:65], v[150:153], v[182:185], v[62:65]
	v_mfma_f32_16x16x32_bf16 v[58:61], v[158:161], v[182:185], v[58:61]
	v_mfma_f32_16x16x32_bf16 v[46:49], v[158:161], v[190:193], v[46:49]
	v_mfma_f32_16x16x32_bf16 v[54:57], v[150:153], v[190:193], v[54:57]
	v_mfma_f32_16x16x32_bf16 v[38:41], v[150:153], v[198:201], v[38:41]
	v_mfma_f32_16x16x32_bf16 v[30:33], v[158:161], v[198:201], v[30:33]
	v_mfma_f32_16x16x32_bf16 v[14:17], v[158:161], v[206:209], v[14:17]
	v_mfma_f32_16x16x32_bf16 v[22:25], v[150:153], v[206:209], v[22:25]
	v_mfma_f32_16x16x32_bf16 v[62:65], v[154:157], v[186:189], v[62:65]
	v_mfma_f32_16x16x32_bf16 v[58:61], v[162:165], v[186:189], v[58:61]
	v_mfma_f32_16x16x32_bf16 v[46:49], v[162:165], v[194:197], v[46:49]
	v_mfma_f32_16x16x32_bf16 v[54:57], v[154:157], v[194:197], v[54:57]
	v_mfma_f32_16x16x32_bf16 v[38:41], v[154:157], v[202:205], v[38:41]
	v_mfma_f32_16x16x32_bf16 v[30:33], v[162:165], v[202:205], v[30:33]
	v_mfma_f32_16x16x32_bf16 v[14:17], v[162:165], v[210:213], v[14:17]
	v_mfma_f32_16x16x32_bf16 v[22:25], v[154:157], v[210:213], v[22:25]
	s_setprio 0
	s_setprio 1
	v_mfma_f32_16x16x32_bf16 v[50:53], v[166:169], v[182:185], v[50:53]
	v_mfma_f32_16x16x32_bf16 v[42:45], v[174:177], v[182:185], v[42:45]
	v_mfma_f32_16x16x32_bf16 v[26:29], v[174:177], v[190:193], v[26:29]
	v_mfma_f32_16x16x32_bf16 v[34:37], v[166:169], v[190:193], v[34:37]
	v_mfma_f32_16x16x32_bf16 v[18:21], v[166:169], v[198:201], v[18:21]
	v_mfma_f32_16x16x32_bf16 v[10:13], v[174:177], v[198:201], v[10:13]
	v_mfma_f32_16x16x32_bf16 v[2:5], v[174:177], v[206:209], v[2:5]
	v_mfma_f32_16x16x32_bf16 v[6:9], v[166:169], v[206:209], v[6:9]
	v_mfma_f32_16x16x32_bf16 v[50:53], v[170:173], v[186:189], v[50:53]
	v_mfma_f32_16x16x32_bf16 v[42:45], v[178:181], v[186:189], v[42:45]
	v_mfma_f32_16x16x32_bf16 v[26:29], v[178:181], v[194:197], v[26:29]
	v_mfma_f32_16x16x32_bf16 v[34:37], v[170:173], v[194:197], v[34:37]
	v_mfma_f32_16x16x32_bf16 v[18:21], v[170:173], v[202:205], v[18:21]
	v_mfma_f32_16x16x32_bf16 v[10:13], v[178:181], v[202:205], v[10:13]
	v_mfma_f32_16x16x32_bf16 v[2:5], v[178:181], v[210:213], v[2:5]
	v_mfma_f32_16x16x32_bf16 v[6:9], v[170:173], v[210:213], v[6:9]
	s_setprio 0
	s_barrier
	s_add_i32 s73, 0, 0x18000
	v_add_u32_e32 v1, s73, v145
	s_add_i32 s74, 0, 0x1c000
	ds_read_b128 v[150:153], v1
	ds_read_b128 v[154:157], v1 offset:1024
	ds_read_b128 v[158:161], v1 offset:2048
	ds_read_b128 v[162:165], v1 offset:3072
	v_add_u32_e32 v1, s74, v145
	ds_read_b128 v[166:169], v1
	ds_read_b128 v[170:173], v1 offset:1024
	ds_read_b128 v[174:177], v1 offset:2048
	ds_read_b128 v[178:181], v1 offset:3072
	s_add_u32 s42, s42, 0x100000
	s_addc_u32 s43, s43, 0
	s_mov_b32 m0, s46
	v_lshl_add_u64 v[220:221], s[42:43], 0, v[130:131]
	ds_read_b128 v[182:185], v149 offset:32768
	ds_read_b128 v[186:189], v149 offset:33792
	ds_read_b128 v[190:193], v149 offset:34816
	ds_read_b128 v[194:197], v149 offset:35840
	ds_read_b128 v[198:201], v149 offset:36864
	ds_read_b128 v[202:205], v149 offset:37888
	ds_read_b128 v[206:209], v149 offset:38912
	ds_read_b128 v[210:213], v149 offset:39936
	global_load_lds_dwordx4 v[220:221], off
	v_lshl_add_u64 v[220:221], s[42:43], 0, v[132:133]
	s_mov_b32 m0, s47
	s_nop 0
	global_load_lds_dwordx4 v[220:221], off
	s_waitcnt vmcnt(8)
	s_waitcnt lgkmcnt(0)
	s_barrier
	s_setprio 1
	s_waitcnt lgkmcnt(0)
	v_mfma_f32_16x16x32_bf16 v[126:129], v[150:153], v[182:185], v[126:129]
	v_mfma_f32_16x16x32_bf16 v[122:125], v[158:161], v[182:185], v[122:125]
	v_mfma_f32_16x16x32_bf16 v[110:113], v[158:161], v[190:193], v[110:113]
	v_mfma_f32_16x16x32_bf16 v[118:121], v[150:153], v[190:193], v[118:121]
	v_mfma_f32_16x16x32_bf16 v[102:105], v[150:153], v[198:201], v[102:105]
	v_mfma_f32_16x16x32_bf16 v[94:97], v[158:161], v[198:201], v[94:97]
	v_mfma_f32_16x16x32_bf16 v[78:81], v[158:161], v[206:209], v[78:81]
	v_mfma_f32_16x16x32_bf16 v[86:89], v[150:153], v[206:209], v[86:89]
	v_mfma_f32_16x16x32_bf16 v[126:129], v[154:157], v[186:189], v[126:129]
	v_mfma_f32_16x16x32_bf16 v[122:125], v[162:165], v[186:189], v[122:125]
	v_mfma_f32_16x16x32_bf16 v[110:113], v[162:165], v[194:197], v[110:113]
	v_mfma_f32_16x16x32_bf16 v[118:121], v[154:157], v[194:197], v[118:121]
	v_mfma_f32_16x16x32_bf16 v[102:105], v[154:157], v[202:205], v[102:105]
	v_mfma_f32_16x16x32_bf16 v[94:97], v[162:165], v[202:205], v[94:97]
	v_mfma_f32_16x16x32_bf16 v[78:81], v[162:165], v[210:213], v[78:81]
	v_mfma_f32_16x16x32_bf16 v[86:89], v[154:157], v[210:213], v[86:89]
	s_setprio 0
	s_setprio 1
	v_mfma_f32_16x16x32_bf16 v[114:117], v[166:169], v[182:185], v[114:117]
	v_mfma_f32_16x16x32_bf16 v[106:109], v[174:177], v[182:185], v[106:109]
	v_mfma_f32_16x16x32_bf16 v[90:93], v[174:177], v[190:193], v[90:93]
	v_mfma_f32_16x16x32_bf16 v[98:101], v[166:169], v[190:193], v[98:101]
	v_mfma_f32_16x16x32_bf16 v[82:85], v[166:169], v[198:201], v[82:85]
	v_mfma_f32_16x16x32_bf16 v[74:77], v[174:177], v[198:201], v[74:77]
	v_mfma_f32_16x16x32_bf16 v[66:69], v[174:177], v[206:209], v[66:69]
	v_mfma_f32_16x16x32_bf16 v[70:73], v[166:169], v[206:209], v[70:73]
	v_mfma_f32_16x16x32_bf16 v[114:117], v[170:173], v[186:189], v[114:117]
	v_mfma_f32_16x16x32_bf16 v[106:109], v[178:181], v[186:189], v[106:109]
	v_mfma_f32_16x16x32_bf16 v[90:93], v[178:181], v[194:197], v[90:93]
	v_mfma_f32_16x16x32_bf16 v[98:101], v[170:173], v[194:197], v[98:101]
	v_mfma_f32_16x16x32_bf16 v[82:85], v[170:173], v[202:205], v[82:85]
	v_mfma_f32_16x16x32_bf16 v[74:77], v[178:181], v[202:205], v[74:77]
	v_mfma_f32_16x16x32_bf16 v[66:69], v[178:181], v[210:213], v[66:69]
	v_mfma_f32_16x16x32_bf16 v[70:73], v[170:173], v[210:213], v[70:73]
	s_setprio 0
	s_barrier
; #define PG8_STAGE(bufoff, gbase, voff) do { _Pragma("unroll") for (int _i = 0; _i < 2; ++_i) \
;         __builtin_amdgcn_global_load_lds((const unsigned*)((const char*)(gbase) + (voff)[_i]), (LAS unsigned*)(lds + (bufoff) + ldsw + _i * 8192), 16, 0, 0); } while (0)
; #define PG8_LDA(dst, b, h) do { _Pragma("unroll") for (int m = 0; m < 4; ++m) _Pragma("unroll") for (int k = 0; k < 2; ++k) dst[m][k] = *(const LAS bf16x8*)(lds + PG8_SA(b, h) + aoff + m * 2048 + k * 1024); } while (0)
; #define PG8_MMA(ai, bj, At, Bt) do { __builtin_amdgcn_s_setprio(1); _Pragma("unroll") for (int m = 0; m < 4; ++m) _Pragma("unroll") for (int n = 0; n < 2; ++n) _Pragma("unroll") for (int k = 0; k < 2; ++k) \
;         acc[ai][bj][m][n] = __builtin_amdgcn_mfma_f32_16x16x32_bf16(Bt[n][k], At[m][k], acc[ai][bj][m][n], 0, 0, 0); __builtin_amdgcn_s_setprio(0); } while (0)
; #define PG8_WAIT_V(n) asm volatile("s_waitcnt vmcnt(" #n ")" ::: "memory")
; #define PG8_WAIT_L(n) asm volatile("s_waitcnt lgkmcnt(" #n ")" ::: "memory")
; #define PG8_BAR __builtin_amdgcn_s_barrier()
; #define PG8_SCHED __builtin_amdgcn_sched_barrier(0)
; template <class Epi, class Sched, bool ALIGN_EPI, bool SP2, bool BPRE = false>
; __device__ __forceinline__ void gemm_phase(LAS unsigned char* lds, const int pitchA, const int pitchB, const Sched& S, const Epi& E) {
;     ...
;         for (int t = 0; t < nt; t += 2) {
;     ...
;             PG8_LDA(At, 1, 1); PG8_STAGE(PG8_SB(1, 0), b3, voffB); PG8_STAGE(PG8_SB(1, 1), b3 + hstepB, voffB); PG8_STAGE(PG8_SA(1, 0), a3, voffA);
;             PG8_WAIT_V(8); PG8_WAIT_L(0); PG8_BAR; PG8_MMA(1, 0, At, B0); PG8_MMA(1, 1, At, B1); PG8_BAR; PG8_SCHED;
	s_add_i32 s42, s73, s37
	v_lshl_add_u64 v[142:143], v[142:143], 0, s[12:13]
	s_mov_b32 m0, s42
	ds_read_b128 v[182:185], v149 offset:49152
	ds_read_b128 v[186:189], v149 offset:50176
	ds_read_b128 v[190:193], v149 offset:51200
	ds_read_b128 v[194:197], v149 offset:52224
	ds_read_b128 v[198:201], v149 offset:53248
	ds_read_b128 v[202:205], v149 offset:54272
	ds_read_b128 v[206:209], v149 offset:55296
	ds_read_b128 v[210:213], v149 offset:56320
	global_load_lds_dwordx4 v[142:143], off
	s_add_i32 m0, s42, 0x2000
	s_add_u32 s40, s40, 0x100080
	v_lshl_add_u64 v[142:143], v[214:215], 0, s[12:13]
	s_addc_u32 s41, s41, 0
	s_add_i32 s42, s74, s37
	global_load_lds_dwordx4 v[142:143], off
	v_lshl_add_u64 v[142:143], s[40:41], 0, v[134:135]
	s_mov_b32 m0, s42
	s_nop 0
	global_load_lds_dwordx4 v[142:143], off
	v_lshl_add_u64 v[142:143], s[40:41], 0, v[136:137]
	s_add_i32 m0, s42, 0x2000
	s_nop 0
	global_load_lds_dwordx4 v[142:143], off
	v_lshl_add_u64 v[142:143], v[216:217], 0, s[12:13]
	s_mov_b32 m0, s50
	s_nop 0
	global_load_lds_dwordx4 v[142:143], off
	v_lshl_add_u64 v[142:143], v[218:219], 0, s[12:13]
	s_mov_b32 m0, s51
	s_nop 0
	global_load_lds_dwordx4 v[142:143], off
	s_waitcnt vmcnt(8)
	s_waitcnt lgkmcnt(0)
	s_barrier
	s_setprio 1
	s_waitcnt lgkmcnt(0)
	v_mfma_f32_16x16x32_bf16 v[62:65], v[150:153], v[182:185], v[62:65]
	v_mfma_f32_16x16x32_bf16 v[58:61], v[158:161], v[182:185], v[58:61]
	v_mfma_f32_16x16x32_bf16 v[46:49], v[158:161], v[190:193], v[46:49]
	v_mfma_f32_16x16x32_bf16 v[54:57], v[150:153], v[190:193], v[54:57]
	v_mfma_f32_16x16x32_bf16 v[38:41], v[150:153], v[198:201], v[38:41]
	v_mfma_f32_16x16x32_bf16 v[30:33], v[158:161], v[198:201], v[30:33]
	v_mfma_f32_16x16x32_bf16 v[14:17], v[158:161], v[206:209], v[14:17]
	v_mfma_f32_16x16x32_bf16 v[22:25], v[150:153], v[206:209], v[22:25]
	v_mfma_f32_16x16x32_bf16 v[62:65], v[154:157], v[186:189], v[62:65]
	v_mfma_f32_16x16x32_bf16 v[58:61], v[162:165], v[186:189], v[58:61]
	v_mfma_f32_16x16x32_bf16 v[46:49], v[162:165], v[194:197], v[46:49]
	v_mfma_f32_16x16x32_bf16 v[54:57], v[154:157], v[194:197], v[54:57]
	v_mfma_f32_16x16x32_bf16 v[38:41], v[154:157], v[202:205], v[38:41]
	v_mfma_f32_16x16x32_bf16 v[30:33], v[162:165], v[202:205], v[30:33]
	v_mfma_f32_16x16x32_bf16 v[14:17], v[162:165], v[210:213], v[14:17]
	v_mfma_f32_16x16x32_bf16 v[22:25], v[154:157], v[210:213], v[22:25]
	s_setprio 0
	s_setprio 1
	v_mfma_f32_16x16x32_bf16 v[50:53], v[166:169], v[182:185], v[50:53]
	v_mfma_f32_16x16x32_bf16 v[42:45], v[174:177], v[182:185], v[42:45]
	v_mfma_f32_16x16x32_bf16 v[26:29], v[174:177], v[190:193], v[26:29]
	v_mfma_f32_16x16x32_bf16 v[34:37], v[166:169], v[190:193], v[34:37]
	v_mfma_f32_16x16x32_bf16 v[18:21], v[166:169], v[198:201], v[18:21]
	v_mfma_f32_16x16x32_bf16 v[10:13], v[174:177], v[198:201], v[10:13]
	v_mfma_f32_16x16x32_bf16 v[2:5], v[174:177], v[206:209], v[2:5]
	v_mfma_f32_16x16x32_bf16 v[6:9], v[166:169], v[206:209], v[6:9]
	v_mfma_f32_16x16x32_bf16 v[50:53], v[170:173], v[186:189], v[50:53]
	v_mfma_f32_16x16x32_bf16 v[42:45], v[178:181], v[186:189], v[42:45]
	v_mfma_f32_16x16x32_bf16 v[26:29], v[178:181], v[194:197], v[26:29]
	v_mfma_f32_16x16x32_bf16 v[34:37], v[170:173], v[194:197], v[34:37]
	v_mfma_f32_16x16x32_bf16 v[18:21], v[170:173], v[202:205], v[18:21]
	v_mfma_f32_16x16x32_bf16 v[10:13], v[178:181], v[202:205], v[10:13]
	v_mfma_f32_16x16x32_bf16 v[2:5], v[178:181], v[210:213], v[2:5]
	v_mfma_f32_16x16x32_bf16 v[6:9], v[170:173], v[210:213], v[6:9]
	s_setprio 0
	s_barrier
	s_add_u32 s38, s38, 0x100
	s_addc_u32 s39, s39, 0
	s_add_u32 s70, s70, 0x100
	s_addc_u32 s71, s71, 0
	s_cmp_ge_i32 s72, s21
	s_mov_b32 s40, s72
	s_cbranch_scc0 .LBB0_765
	s_and_b64 vcc, exec, s[16:17]
	s_cbranch_vccz .LBB0_768
	s_barrier
